# code placement: one s_nop before the attention loop head (loop and all later code shifted by 4 bytes; attention loop at 0 mod 8, later GEMM loops back at their baseline 4 mod 8 phase)
# speedup vs baseline: 1.0012x; 1.0012x over previous
.LBB0_853:
	s_and_b64 vcc, exec, s[0:1]
	s_cbranch_vccz .LBB0_820
	s_ashr_i32 s14, s49, 5
	s_ashr_i32 s15, s14, 31
	s_lshl_b32 s0, s49, 8
	s_lshl_b64 s[42:43], s[14:15], 11
	s_and_b32 s0, s0, 0x700
	s_or_b32 s42, s42, s0
	s_mul_i32 s0, s43, 0x600
	s_mul_hi_u32 s1, s42, 0x600
	s_bfe_u32 s4, s49, 0x20003
	s_add_i32 s1, s1, s0
	s_mul_i32 s0, s42, 0x600
	s_add_u32 s0, s84, s0
	s_addc_u32 s1, s85, s1
	s_mul_i32 s2, s4, 0x180
	s_add_u32 s16, s0, s2
	s_addc_u32 s17, s1, 0
	v_readlane_b32 s0, v251, 48
	v_readlane_b32 s1, v251, 49
	s_add_u32 s2, s0, s2
	s_addc_u32 s8, s1, 0
	s_lshl_b32 s7, s4, 7
	s_lshl_b32 s0, s4, 8
	v_readlane_b32 s10, v253, 7
	v_mov_b32_e32 v170, v0
	v_readlane_b32 s11, v253, 8
	s_add_u32 s9, s10, s0
	s_addc_u32 s10, s11, 0
	v_ashrrev_i32_e32 v161, 6, v170
	v_and_b32_e32 v172, 31, v170
	v_and_b32_e32 v2, 0x3fffffc0, v170
	s_add_i32 s1, 0, 0x14000
	v_lshlrev_b32_e32 v160, 5, v161
	v_bfe_u32 v173, v170, 5, 1
	v_lshl_add_u32 v64, v2, 2, s1
	v_or_b32_e32 v4, v160, v172
	s_waitcnt lgkmcnt(0)
	v_mov_b64_e32 v[2:3], s[16:17]
	s_movk_i32 s11, 0x600
	v_mad_i64_i32 v[2:3], s[16:17], v4, s11, v[2:3]
	v_lshlrev_b32_e32 v62, 4, v173
	v_mov_b32_e32 v63, v99
	v_lshl_add_u64 v[6:7], v[2:3], 0, v[62:63]
	v_lshlrev_b32_e32 v2, 12, v161
	s_add_i32 s1, 0, 0x14800
	v_lshlrev_b32_e32 v3, 7, v172
	global_load_dwordx4 v[128:131], v[6:7], off
	global_load_dwordx4 v[124:127], v[6:7], off offset:32
	global_load_dwordx4 v[120:123], v[6:7], off offset:64
	global_load_dwordx4 v[116:119], v[6:7], off offset:96
	global_load_dwordx4 v[112:115], v[6:7], off offset:128
	global_load_dwordx4 v[108:111], v[6:7], off offset:160
	global_load_dwordx4 v[104:107], v[6:7], off offset:192
	global_load_dwordx4 v[100:103], v[6:7], off offset:224
	v_add3_u32 v51, s1, v2, v3
	global_load_dwordx4 v[2:5], v[6:7], off offset:256
	global_load_dwordx4 v[132:135], v[6:7], off offset:288
	global_load_dwordx4 v[136:139], v[6:7], off offset:320
	global_load_dwordx4 v[140:143], v[6:7], off offset:352
	v_bitop3_b32 v8, v173, v170, 7 bitop3:0x78
	v_lshl_add_u32 v8, v8, 4, v51
	v_lshlrev_b32_e32 v14, 4, v170
	v_and_b32_e32 v50, 0x70, v14
	s_movk_i32 s1, 0x60
	s_movk_i32 s18, 0x180
	s_lshl_b32 s12, s14, 8
	s_add_i32 s0, s12, 0x4000
	s_lshl_b32 s13, s14, 11
	s_cmp_lg_u32 0, -1
	s_mul_i32 s15, s14, 0x60000
	s_cselect_b32 s14, 0, 0
	s_mov_b32 s100, 0xaaaaaaab
	v_lshrrev_b32_e32 v38, 6, v0
	v_lshl_add_u32 v39, v38, 7, v0
	v_mul_hi_u32 v40, v39, s100
	v_lshrrev_b32_e32 v40, 4, v40
	v_mul_u32_u24_e32 v41, 24, v40
	v_sub_u32_e32 v41, v39, v41
	v_and_b32_e32 v42, 7, v40
	v_xor_b32_e32 v41, v41, v42
	v_mul_u32_u24_e32 v42, 0x600, v40
	v_lshl_add_u32 v180, v41, 4, v42
	v_add_u32_e32 v39, 64, v39
	v_mul_hi_u32 v40, v39, s100
	v_lshrrev_b32_e32 v40, 4, v40
	v_mul_u32_u24_e32 v41, 24, v40
	v_sub_u32_e32 v41, v39, v41
	v_and_b32_e32 v42, 7, v40
	v_xor_b32_e32 v41, v41, v42
	v_mul_u32_u24_e32 v42, 0x600, v40
	v_lshl_add_u32 v181, v41, 4, v42
	v_add_u32_e32 v39, 64, v39
	v_mul_hi_u32 v40, v39, s100
	v_lshrrev_b32_e32 v40, 4, v40
	v_mul_u32_u24_e32 v41, 24, v40
	v_sub_u32_e32 v41, v39, v41
	v_and_b32_e32 v42, 7, v40
	v_xor_b32_e32 v41, v41, v42
	v_mul_u32_u24_e32 v42, 0x600, v40
	v_lshl_add_u32 v182, v41, 4, v42
	v_lshl_add_u32 v39, v38, 6, v0
	v_and_b32_e32 v40, 3, v39
	v_lshlrev_b32_e32 v40, 4, v40
	v_bfe_u32 v41, v39, 5, 2
	v_lshl_or_b32 v40, v41, 6, v40
	v_bfe_u32 v41, v39, 2, 2
	v_lshl_or_b32 v40, v41, 10, v40
	v_bfe_u32 v41, v39, 7, 1
	v_lshl_or_b32 v40, v41, 12, v40
	v_bfe_u32 v41, v39, 4, 1
	v_lshl_or_b32 v40, v41, 13, v40
	v_bfe_u32 v41, v39, 8, 2
	v_lshl_or_b32 v178, v41, 14, v40
	v_add_u32_e32 v39, 64, v39
	v_and_b32_e32 v40, 3, v39
	v_lshlrev_b32_e32 v40, 4, v40
	v_bfe_u32 v41, v39, 5, 2
	v_lshl_or_b32 v40, v41, 6, v40
	v_bfe_u32 v41, v39, 2, 2
	v_lshl_or_b32 v40, v41, 10, v40
	v_bfe_u32 v41, v39, 7, 1
	v_lshl_or_b32 v40, v41, 12, v40
	v_bfe_u32 v41, v39, 4, 1
	v_lshl_or_b32 v40, v41, 13, v40
	v_bfe_u32 v41, v39, 8, 2
	v_lshl_or_b32 v179, v41, 14, v40
	v_readfirstlane_b32 s101, v38
	s_nop 1
	s_mul_i32 vcc_lo, s101, 0xc00
	s_lshl_b32 vcc_hi, s101, 11
	s_ashr_i32 s101, s0, 31
	s_mov_b32 s100, s0
	s_lshl_b64 s[16:17], s[100:101], 10
	s_add_u32 s16, s9, s16
	s_addc_u32 s17, s10, s17
	s_mul_hi_i32 s101, s0, 0x600
	s_add_i32 s100, s15, 0x1800000
	s_add_u32 s100, s2, s100
	s_addc_u32 s101, s8, s101
	s_add_i32 m0, vcc_hi, 0x0
	s_nop 0
	global_load_lds_dwordx4 v178, s[16:17]
	s_add_i32 m0, vcc_hi, 0x400
	s_nop 0
	global_load_lds_dwordx4 v179, s[16:17]
	s_add_i32 m0, vcc_lo, 0x8000
	s_nop 0
	global_load_lds_dwordx4 v180, s[100:101]
	s_add_i32 m0, vcc_lo, 0x8400
	s_nop 0
	global_load_lds_dwordx4 v181, s[100:101]
	s_add_i32 m0, vcc_lo, 0x8800
	s_nop 0
	global_load_lds_dwordx4 v182, s[100:101]
	s_add_u32 s16, s16, 0x10000
	s_addc_u32 s17, s17, 0
	s_add_u32 s100, s100, 0x18000
	s_addc_u32 s101, s101, 0
	s_add_i32 m0, vcc_hi, 0x4000
	s_nop 0
	global_load_lds_dwordx4 v178, s[16:17]
	s_add_i32 m0, vcc_hi, 0x4400
	s_nop 0
	global_load_lds_dwordx4 v179, s[16:17]
	s_add_i32 m0, vcc_lo, 0xe000
	s_nop 0
	global_load_lds_dwordx4 v180, s[100:101]
	s_add_i32 m0, vcc_lo, 0xe400
	s_nop 0
	global_load_lds_dwordx4 v181, s[100:101]
	s_add_i32 m0, vcc_lo, 0xe800
	s_nop 0
	global_load_lds_dwordx4 v182, s[100:101]
	s_mov_b32 s101, vcc_lo
	s_mov_b32 s100, vcc_hi
	v_and_b32_e32 v171, 63, v170
	v_mul_u32_u24_e32 v55, 0x180, v172
	v_or_b32_e32 v52, 32, v62
	v_bitop3_b32 v56, v52, v55, v50 bitop3:0xde
	v_add_u32_e32 v184, 0, v56
	v_or_b32_e32 v53, 64, v62
	v_or_b32_e32 v54, 0x60, v62
	s_mov_b32 s68, s69
	s_mov_b32 s70, s69
	s_mov_b32 s71, s69
	s_mov_b32 s72, s69
	s_mov_b32 s73, s69
	s_mov_b32 s74, s69
	s_mov_b32 s75, s69
	s_mov_b32 s76, s69
	s_mov_b32 s77, s69
	s_mov_b32 s78, s69
	s_mov_b32 s79, s69
	s_mov_b32 s80, s69
	s_mov_b32 s81, s69
	s_mov_b32 s82, s69
	s_mov_b32 s83, s69
	v_lshl_add_u32 v197, v172, 2, v64
	v_add_u32_e32 v193, v64, v62
	v_mov_b32_e32 v212, 0x358637bd
	v_mov_b32_e32 v200, 0xff
	v_mov_b32_e32 v202, 0x1b00
	v_mov_b32_e32 v201, 0x600
	v_mov_b32_e32 v203, 0x260
	v_mov_b32_e32 v169, v99
	v_mov_b32_e32 v163, v99
	v_mov_b32_e32 v165, v99
	v_mov_b32_e32 v167, v99
	v_cmp_gt_u32_e64 s[38:39], 32, v171
	v_mov_b32_e32 v198, 0
	s_waitcnt vmcnt(10)
	ds_write_b128 v8, v[2:5]
	v_bitop3_b32 v8, v62, v50, 32 bitop3:0x36
	v_add_u32_e32 v176, v51, v8
	v_bitop3_b32 v8, v62, v50, 64 bitop3:0x36
	v_add_u32_e32 v177, v51, v8
	ds_write_b128 v176, v[132:135]
	ds_write_b128 v177, v[136:139]
	v_bitop3_b32 v6, v62, v50, s1 bitop3:0x36
	v_add_u32_e32 v175, v51, v6
	s_mov_b32 s1, 0x2aaaaaab
	ds_write_b128 v175, v[140:143]
	v_ashrrev_i32_e32 v2, 4, v170
	v_and_b32_e32 v5, 0xfffff0, v2
	v_lshlrev_b32_e32 v6, 1, v2
	v_and_or_b32 v5, v6, 8, v5
	v_lshrrev_b32_e32 v6, 1, v2
	v_and_b32_e32 v7, 3, v2
	v_and_or_b32 v6, v6, 4, v7
	v_add_u32_e32 v7, 32, v2
	v_and_b32_e32 v8, 0xfffff0, v7
	v_lshlrev_b32_e32 v7, 1, v7
	v_lshlrev_b32_e32 v3, 3, v170
	v_and_or_b32 v7, v7, 8, v8
	v_and_b32_e32 v4, 0x78, v3
	v_lshrrev_b32_e32 v5, 1, v5
	v_bfe_u32 v3, v3, 5, 2
	v_lshrrev_b32_e32 v7, 1, v7
	v_or_b32_e32 v5, v5, v3
	v_or_b32_e32 v3, v7, v3
	v_mul_hi_i32 v7, v170, s1
	v_lshrrev_b32_e32 v8, 31, v7
	v_ashrrev_i32_e32 v7, 2, v7
	v_add_u32_e32 v7, v7, v8
	v_mul_lo_u32 v8, v7, 24
	v_sub_u32_e32 v8, v170, v8
	v_mul_lo_u32 v9, v7, s11
	v_lshl_add_u32 v162, v8, 4, v9
	v_mul_lo_u32 v9, v7, s18
	v_bitop3_b32 v7, v7, v8, 7 bitop3:0x6c
	v_lshl_add_u32 v15, v7, 4, v9
	v_add_u32_e32 v7, 0x200, v170
	v_mul_hi_i32 v8, v7, s1
	v_lshrrev_b32_e32 v9, 31, v8
	v_ashrrev_i32_e32 v8, 2, v8
	v_add_u32_e32 v8, v8, v9
	v_mul_lo_u32 v9, v8, 24
	v_sub_u32_e32 v7, v7, v9
	v_mul_lo_u32 v9, v8, s11
	v_lshl_add_u32 v164, v7, 4, v9
	v_mul_lo_u32 v9, v8, s18
	v_bitop3_b32 v7, v8, v7, 7 bitop3:0x6c
	v_lshl_add_u32 v24, v7, 4, v9
	v_add_u32_e32 v7, 0x400, v170
	v_mul_hi_i32 v8, v7, s1
	v_lshrrev_b32_e32 v9, 31, v8
	v_ashrrev_i32_e32 v8, 2, v8
	v_add_u32_e32 v8, v8, v9
	v_mul_lo_u32 v9, v8, 24
	v_sub_u32_e32 v7, v7, v9
	v_mul_lo_u32 v9, v8, s11
	v_lshlrev_b32_e32 v4, 1, v4
	v_lshl_add_u32 v166, v7, 4, v9
	v_mul_lo_u32 v9, v8, s18
	v_bitop3_b32 v7, v8, v7, 7 bitop3:0x6c
	s_ashr_i32 s1, s0, 31
	v_lshlrev_b32_e32 v6, 6, v6
	v_lshlrev_b32_e32 v3, 9, v3
	v_lshl_add_u32 v25, v7, 4, v9
	v_and_b32_e32 v7, 48, v4
	s_lshl_b64 s[16:17], s[0:1], 10
	v_or3_b32 v27, v3, v6, v7
	v_lshl_or_b32 v98, v2, 10, v4
	v_lshlrev_b32_e32 v2, 3, v171
	v_and_b32_e32 v3, 0xc0, v14
	v_lshlrev_b32_e32 v4, 1, v170
	s_add_u32 s16, s9, s16
	v_lshlrev_b32_e32 v5, 9, v5
	v_and_or_b32 v3, v2, 24, v3
	v_and_b32_e32 v4, 32, v4
	v_and_b32_e32 v2, 0x100, v2
	s_addc_u32 s17, s10, s17
	v_or3_b32 v26, v5, v6, v7
	v_or3_b32 v63, v3, v4, v2
	s_add_i32 s15, s15, 0x1800000
	s_mul_hi_i32 s1, s0, 0x600
	s_add_u32 s0, s2, s15
	v_add_u32_e32 v168, 0x8000, v98
	s_addc_u32 s1, s8, s1
	s_movk_i32 s0, 0x70
	v_bitop3_b32 v61, v62, v14, s0 bitop3:0x78
	s_movk_i32 s0, 0x80
	v_add_u32_e32 v192, v51, v61
	v_add_u32_e32 v174, s14, v63
	s_mov_b32 s11, -1
	v_mov_b32_e32 v2, 0x3000
	v_mad_u32_u24 v60, v172, s18, v2
	v_bitop3_b32 v2, v62, v55, v50 bitop3:0xde
	v_add_u32_e32 v183, 0, v2
	s_waitcnt vmcnt(5) lgkmcnt(0)
	s_barrier
	ds_read_b128 v[18:21], v183 offset:32768
	ds_read_b128 v[22:25], v183 offset:45056
	ds_read_b128 v[56:59], v184 offset:32768
	ds_read_b128 v[68:71], v184 offset:45056
	s_waitcnt lgkmcnt(3)
	v_mfma_f32_32x32x16_bf16 v[34:49], v[18:21], v[128:131], 0
	v_bitop3_b32 v66, v52, v60, v50 bitop3:0xde
	v_bitop3_b32 v52, v53, v55, v50 bitop3:0xde
	v_add_u32_e32 v185, 0, v52
	v_bitop3_b32 v52, v54, v55, v50 bitop3:0xde
	v_add_u32_e32 v186, 0, v52
	v_bitop3_b32 v67, v53, v60, v50 bitop3:0xde
	v_mov_b64_e32 v[2:3], s[68:69]
	s_waitcnt lgkmcnt(2)
	v_mfma_f32_32x32x16_bf16 v[18:33], v[22:25], v[128:131], 0
	v_mov_b64_e32 v[4:5], s[70:71]
	v_mov_b64_e32 v[6:7], s[72:73]
	v_mov_b64_e32 v[8:9], s[74:75]
	v_mov_b64_e32 v[10:11], s[76:77]
	v_mov_b64_e32 v[12:13], s[78:79]
	v_mov_b64_e32 v[14:15], s[80:81]
	v_mov_b64_e32 v[16:17], s[82:83]
	s_waitcnt lgkmcnt(1)
	v_mfma_f32_32x32x16_bf16 v[34:49], v[56:59], v[124:127], v[34:49]
	ds_read_b128 v[56:59], v185 offset:32768
	s_movk_i32 s82, 0x100
	ds_read_b128 v[74:77], v192
	v_bitop3_b32 v65, v62, v60, v50 bitop3:0xde
	v_readlane_b32 s80, v254, 41
	v_readlane_b32 s74, v254, 44
	v_readlane_b32 s81, v254, 42
	s_waitcnt lgkmcnt(2)
	v_mfma_f32_32x32x16_bf16 v[18:33], v[68:71], v[124:127], v[18:33]
	ds_read_b128 v[68:71], v185 offset:45056
	v_add_u32_e32 v226, 0, v65
	v_readlane_b32 s75, v254, 45
	v_readlane_b32 s83, v254, 43
	s_movk_i32 s81, 0x300
	v_add_u32_e32 v225, 0, v66
	v_add_u32_e32 v224, 0, v67
	s_waitcnt lgkmcnt(2)
	v_mfma_f32_32x32x16_bf16 v[34:49], v[56:59], v[120:123], v[34:49]
	ds_read_b128 v[56:59], v186 offset:32768
	s_waitcnt lgkmcnt(1)
	v_mfma_f32_32x32x16_bf16 v[18:33], v[68:71], v[120:123], v[18:33]
	v_bitop3_b32 v68, v54, v60, v50 bitop3:0xde
	ds_read_b128 v[52:55], v186 offset:45056
	v_add_u32_e32 v223, 0, v68
	s_waitcnt lgkmcnt(1)
	v_mfma_f32_32x32x16_bf16 v[34:49], v[56:59], v[116:119], v[34:49]
	v_bitop3_b32 v56, v62, v50, s0 bitop3:0x36
	v_add_u32_e32 v69, v56, v60
	s_movk_i32 s0, 0xa0
	v_add_u32_e32 v222, 0, v69
	s_waitcnt lgkmcnt(0)
	v_mfma_f32_32x32x16_bf16 v[18:33], v[52:55], v[116:119], v[18:33]
	v_mad_u32_u24 v52, v172, s18, v56
	v_add_u32_e32 v187, 0, v52
	ds_read_b128 v[52:55], v187 offset:32768
	ds_read_b128 v[56:59], v187 offset:45056
	s_waitcnt lgkmcnt(0)
	v_mfma_f32_32x32x16_bf16 v[18:33], v[56:59], v[112:115], v[18:33]
	v_bitop3_b32 v56, v62, v50, s0 bitop3:0x36
	v_add_u32_e32 v70, v56, v60
	s_movk_i32 s0, 0xc0
	v_add_u32_e32 v221, 0, v70
	v_mfma_f32_32x32x16_bf16 v[34:49], v[52:55], v[112:115], v[34:49]
	v_mad_u32_u24 v52, v172, s18, v56
	v_add_u32_e32 v188, 0, v52
	ds_read_b128 v[52:55], v188 offset:32768
	ds_read_b128 v[56:59], v188 offset:45056
	s_waitcnt lgkmcnt(0)
	v_mfma_f32_32x32x16_bf16 v[18:33], v[56:59], v[108:111], v[18:33]
	v_bitop3_b32 v56, v62, v50, s0 bitop3:0x36
	v_add_u32_e32 v71, v56, v60
	s_movk_i32 s0, 0xe0
	v_add_u32_e32 v220, 0, v71
	v_mfma_f32_32x32x16_bf16 v[34:49], v[52:55], v[108:111], v[34:49]
	v_mad_u32_u24 v52, v172, s18, v56
	v_add_u32_e32 v189, 0, v52
	ds_read_b128 v[52:55], v189 offset:32768
	ds_read_b128 v[56:59], v189 offset:45056
	s_waitcnt lgkmcnt(0)
	v_mfma_f32_32x32x16_bf16 v[18:33], v[56:59], v[104:107], v[18:33]
	v_bitop3_b32 v56, v62, v50, s0 bitop3:0x36
	v_add_u32_e32 v72, v56, v60
	s_movk_i32 s0, 0x120
	v_bitop3_b32 v51, v62, v50, s0 bitop3:0x36
	s_movk_i32 s0, 0x140
	v_add_u32_e32 v219, 0, v72
	v_mfma_f32_32x32x16_bf16 v[34:49], v[52:55], v[104:107], v[34:49]
	v_mad_u32_u24 v52, v172, s18, v56
	v_add_u32_e32 v190, 0, v52
	ds_read_b128 v[52:55], v190 offset:32768
	ds_read_b128 v[56:59], v190 offset:45056
	s_waitcnt lgkmcnt(0)
	v_mfma_f32_32x32x16_bf16 v[18:33], v[56:59], v[100:103], v[18:33]
	v_bitop3_b32 v56, v62, v50, s82 bitop3:0x36
	v_add_u32_e32 v73, v56, v60
	v_add_u32_e32 v218, 0, v73
	v_mfma_f32_32x32x16_bf16 v[34:49], v[52:55], v[100:103], v[34:49]
	v_mad_u32_u24 v52, v172, s18, v56
	v_add_u32_e32 v191, 0, v52
	ds_read_b128 v[52:55], v191 offset:32768
	ds_read_b128 v[56:59], v191 offset:45056
	s_waitcnt lgkmcnt(1)
	v_mfma_f32_32x32x16_bf16 v[34:49], v[52:55], v[74:77], v[34:49]
	v_mad_u32_u24 v52, v172, s18, v51
	v_add_u32_e32 v194, 0, v52
	ds_read_b128 v[52:55], v194 offset:32768
	s_waitcnt lgkmcnt(1)
	v_mfma_f32_32x32x16_bf16 v[18:33], v[56:59], v[74:77], v[18:33]
	ds_read_b128 v[56:59], v194 offset:45056
	ds_read_b128 v[76:79], v176
	v_add_u32_e32 v74, v51, v60
	v_bitop3_b32 v51, v62, v50, s0 bitop3:0x36
	s_movk_i32 s0, 0x160
	v_bitop3_b32 v50, v62, v50, s0 bitop3:0x36
	v_add_u32_e32 v75, v51, v60
	v_add_u32_e32 v217, 0, v74
	s_waitcnt lgkmcnt(0)
	v_mfma_f32_32x32x16_bf16 v[34:49], v[52:55], v[76:79], v[34:49]
	v_mad_u32_u24 v52, v172, s18, v51
	v_add_u32_e32 v195, 0, v52
	ds_read_b128 v[52:55], v195 offset:32768
	v_mad_u32_u24 v51, v172, s18, v50
	v_add_u32_e32 v196, 0, v51
	v_add_u32_e32 v216, 0, v75
	v_mfma_f32_32x32x16_bf16 v[18:33], v[56:59], v[76:79], v[18:33]
	ds_read_b128 v[56:59], v195 offset:45056
	ds_read_b128 v[76:79], v177
	s_waitcnt lgkmcnt(0)
	v_mfma_f32_32x32x16_bf16 v[34:49], v[52:55], v[76:79], v[34:49]
	v_mfma_f32_32x32x16_bf16 v[18:33], v[56:59], v[76:79], v[18:33]
	ds_read_b128 v[54:57], v196 offset:32768
	v_add_u32_e32 v76, v50, v60
	ds_read_b128 v[50:53], v196 offset:45056
	ds_read_b128 v[58:61], v175
	v_add_u32_e32 v215, 0, v76
	s_waitcnt lgkmcnt(0)
	v_mfma_f32_32x32x16_bf16 v[34:49], v[54:57], v[58:61], v[34:49]
	v_mfma_f32_32x32x16_bf16 v[18:33], v[50:53], v[58:61], v[18:33]
	s_nop 10
	v_max_f32_e32 v50, v35, v35
	v_max_f32_e32 v51, v34, v34
	v_max_f32_e32 v50, v51, v50
	v_max3_f32 v50, v50, v36, v37
	v_max3_f32 v50, v50, v38, v39
	v_max3_f32 v50, v50, v40, v41
	v_max3_f32 v50, v50, v42, v43
	v_max3_f32 v50, v50, v44, v45
	v_max3_f32 v50, v50, v46, v47
	v_max3_f32 v50, v50, v48, v49
	v_max3_f32 v50, v50, v18, v19
	v_max3_f32 v50, v50, v20, v21
	v_max3_f32 v50, v50, v22, v23
	v_max3_f32 v50, v50, v24, v25
	v_max3_f32 v50, v50, v26, v27
	v_max3_f32 v50, v50, v28, v29
	v_max3_f32 v50, v50, v30, v31
	v_max3_f32 v50, v50, v32, v33
	v_mov_b32_e32 v51, v50
	s_nop 1
	v_permlane32_swap_b32_e32 v50, v51
	v_max_f32_e32 v51, v51, v51
	v_max_f32_e32 v50, v50, v50
	v_max_f32_e32 v50, v50, v51
	v_add_f32_e32 v51, 0x7149f2ca, v50
	v_max_f32_e32 v50, 0xf149f2ca, v50
	v_cmp_ge_f32_e32 vcc, s5, v51
	v_sub_f32_e32 v51, 0xf149f2ca, v50
	s_cmp_eq_u64 vcc, exec
	v_mul_f32_e32 v51, 0x3dd53b94, v51
	s_cselect_b64 vcc, -1, 0
	v_exp_f32_e32 v51, v51
	s_add_i32 s0, s12, 0x4040
	v_mov_b32_e32 v52, 0xf149f2ca
	s_ashr_i32 s1, s0, 31
	v_cndmask_b32_e32 v214, v50, v52, vcc
	s_lshl_b64 s[16:17], s[0:1], 10
	v_mul_f32_e32 v50, 0xbdd53b94, v214
	s_add_u32 s16, s9, s16
	v_cndmask_b32_e64 v213, v51, 1.0, vcc
	v_mov_b32_e32 v51, v50
	s_addc_u32 s17, s10, s17
	s_mul_hi_i32 s1, s0, 0x600
	s_mulk_i32 s0, 0x600
	v_fmamk_f32 v34, v34, 0x3dd53b94, v50
	v_fmamk_f32 v35, v35, 0x3dd53b94, v50
	v_fmamk_f32 v36, v36, 0x3dd53b94, v50
	v_fmamk_f32 v37, v37, 0x3dd53b94, v50
	v_fmac_f32_e32 v51, 0x3dd53b94, v49
	s_add_u32 s0, s2, s0
	v_pk_fma_f32 v[138:139], v[32:33], s[30:31], v[50:51] op_sel_hi:[1,0,0]
	v_pk_fma_f32 v[140:141], v[30:31], s[30:31], v[50:51] op_sel_hi:[1,0,0]
	v_pk_fma_f32 v[146:147], v[28:29], s[30:31], v[50:51] op_sel_hi:[1,0,0]
	v_pk_fma_f32 v[132:133], v[26:27], s[30:31], v[50:51] op_sel_hi:[1,0,0]
	v_pk_fma_f32 v[134:135], v[24:25], s[30:31], v[50:51] op_sel_hi:[1,0,0]
	v_pk_fma_f32 v[136:137], v[22:23], s[30:31], v[50:51] op_sel_hi:[1,0,0]
	v_pk_fma_f32 v[142:143], v[20:21], s[30:31], v[50:51] op_sel_hi:[1,0,0]
	v_pk_fma_f32 v[144:145], v[18:19], s[30:31], v[50:51] op_sel_hi:[1,0,0]
	v_exp_f32_e32 v153, v34
	v_exp_f32_e32 v154, v35
	v_exp_f32_e32 v230, v36
	v_exp_f32_e32 v231, v37
	s_addc_u32 s1, s8, s1
	v_fmamk_f32 v38, v38, 0x3dd53b94, v50
	v_fmamk_f32 v39, v39, 0x3dd53b94, v50
	v_fmamk_f32 v40, v40, 0x3dd53b94, v50
	v_fmamk_f32 v41, v41, 0x3dd53b94, v50
	v_fmamk_f32 v42, v42, 0x3dd53b94, v50
	v_fmamk_f32 v43, v43, 0x3dd53b94, v50
	v_fmamk_f32 v44, v44, 0x3dd53b94, v50
	v_fmamk_f32 v45, v45, 0x3dd53b94, v50
	v_fmamk_f32 v46, v46, 0x3dd53b94, v50
	v_fmamk_f32 v47, v47, 0x3dd53b94, v50
	v_fmamk_f32 v48, v48, 0x3dd53b94, v50
	v_exp_f32_e32 v232, v38
	v_exp_f32_e32 v233, v39
	v_exp_f32_e32 v155, v40
	v_exp_f32_e32 v229, v41
	v_exp_f32_e32 v151, v42
	v_exp_f32_e32 v156, v43
	v_exp_f32_e32 v157, v44
	v_exp_f32_e32 v158, v45
	v_exp_f32_e32 v148, v46
	v_exp_f32_e32 v149, v47
	v_exp_f32_e32 v150, v48
	v_exp_f32_e32 v159, v51
	s_addk_i32 s14, 0x4000
	v_add_u32_e32 v199, s14, v63
	v_mov_b64_e32 v[64:65], v[16:17]
	v_mov_b64_e32 v[48:49], v[16:17]
	v_mov_b64_e32 v[32:33], v[16:17]
	s_addk_i32 s12, 0x4080
	s_sub_i32 s13, s13, 64
	v_mov_b64_e32 v[62:63], v[14:15]
	v_mov_b64_e32 v[60:61], v[12:13]
	v_mov_b64_e32 v[58:59], v[10:11]
	v_mov_b64_e32 v[56:57], v[8:9]
	v_mov_b64_e32 v[54:55], v[6:7]
	v_mov_b64_e32 v[52:53], v[4:5]
	v_mov_b64_e32 v[50:51], v[2:3]
	v_mov_b64_e32 v[46:47], v[14:15]
	v_mov_b64_e32 v[44:45], v[12:13]
	v_mov_b64_e32 v[42:43], v[10:11]
	v_mov_b64_e32 v[40:41], v[8:9]
	v_mov_b64_e32 v[38:39], v[6:7]
	v_mov_b64_e32 v[36:37], v[4:5]
	v_mov_b64_e32 v[34:35], v[2:3]
	v_mov_b64_e32 v[30:31], v[14:15]
	v_mov_b64_e32 v[28:29], v[12:13]
	v_mov_b64_e32 v[26:27], v[10:11]
	v_mov_b64_e32 v[24:25], v[8:9]
	v_mov_b64_e32 v[22:23], v[6:7]
	v_mov_b64_e32 v[20:21], v[4:5]
	v_mov_b64_e32 v[18:19], v[2:3]
	s_mov_b32 s14, s16
	s_mov_b32 s15, s17
	s_waitcnt vmcnt(0) lgkmcnt(0)
	s_barrier
	s_nop 0
